# baseline (speedup 1.0000x reference)
; DEV float log_gamma(int h) { return log1pf(-exp2f(-5.0f - (float)h)); }
; DEV void ret_out_item(const Params& p, int l, int item, unsigned char* smem) {
;   const int half = 1, sitem = item, h = sitem & 3, n = (sitem >> 2) & 63, b = sitem >> 8;
;   const int tid = tidx(), w = tid >> 6, lane = tid & 63, fr = lane & 15, fq = lane >> 4;
;   const int r0w = w * RW;
;   u16* sST = (u16*)(smem + L_ST);
;   u16* sP = (u16*)(smem + L_PW) + w * RW * VS;
;   const u16* base = p.proj + ((size_t)b * SEQ + n * 128) * DIN;
;   const float lg = log_gamma(h);
;   bf16x8 qf[MT][4];
;   load_qfrags(base + (size_t)r0w * DIN + C_RQ + h * 128, qf, fr, fq);
;   f32x4 o[MT][8];
; #pragma unroll
;   for (int mt = 0; mt < MT; ++mt)
; #pragma unroll
;     for (int nt = 0; nt < 8; ++nt) o[mt][nt] = (f32x4){0.f, 0.f, 0.f, 0.f};
;   uint4 kq0, kq1, vq0, vq1;
;   kv_load(base + C_RK + h * 128, base + C_RV + h * 128, kq0, kq1, vq0, vq1, tid);
;   __syncthreads();
;   {
;     const float4* st = (const float4*)(p.prev + (size_t)sitem * 16384);
;     for (int c = tid; c < 128 * 32; c += NT) {
.LBB0_341:
	v_readfirstlane_b32 s1, v160
	s_ashr_i32 s0, s4, 8
	s_andn2_b32 s1, s1, 63
	v_or_b32_e32 v38, s1, v161
	s_ashr_i32 s1, s0, 31
	s_lshl_b64 s[6:7], s[0:1], 13
	s_lshl_b32 s0, s4, 5
	s_and_b32 s0, s0, 0x1f80
	s_or_b32 s6, s6, s0
	s_and_b32 s28, s4, 3
	s_mul_i32 s0, s7, 0x2800
	v_ashrrev_i32_e32 v0, 2, v38
	s_mul_hi_u32 s1, s6, 0x2800
	v_and_b32_e32 v80, -16, v0
	s_add_i32 s1, s1, s0
	s_mul_i32 s0, s6, 0x2800
	v_cvt_f32_ubyte0_e32 v0, s28
	s_add_u32 s10, s76, s0
	v_sub_f32_e32 v39, 0xc0a00000, v0
	s_mov_b32 s0, 0xc2fc0000
	s_addc_u32 s11, s77, s1
	v_cmp_gt_f32_e32 vcc, s0, v39
	v_and_b32_e32 v90, 15, v38
	s_and_b64 s[0:1], vcc, exec
	v_mov_b64_e32 v[0:1], s[10:11]
	s_cselect_b32 s5, 0xffffffc0, 0
	v_mad_i64_i32 v[0:1], s[0:1], v80, s88, v[0:1]
	s_lshl_b32 s18, s28, 8
	v_mul_u32_u24_e32 v2, 0x1400, v90
	v_bfe_u32 v92, v38, 4, 2
	v_lshl_add_u64 v[0:1], v[0:1], 0, s[18:19]
	v_lshlrev_b32_e32 v128, 1, v2
	v_lshlrev_b32_e32 v18, 3, v38
	v_lshl_add_u64 v[0:1], v[0:1], 0, v[128:129]
	v_lshlrev_b32_e32 v128, 4, v92
	v_and_b32_e32 v18, 0x78, v18
	v_and_b32_e32 v43, 63, v38
	v_lshl_add_u64 v[0:1], v[0:1], 0, v[128:129]
	s_add_u32 s0, s10, s18
	v_lshlrev_b32_e32 v128, 1, v18
	v_mul_u32_u24_e32 v18, 0x1400, v43
	s_addc_u32 s1, s11, 0
	v_add_u32_e32 v28, 0x200, v38
	v_lshlrev_b32_e32 v32, 1, v18
	v_mov_b32_e32 v33, v129
	v_lshl_add_u64 v[22:23], s[0:1], 0, v[32:33]
	v_ashrrev_i32_e32 v18, 3, v38
	v_ashrrev_i32_e32 v33, 4, v28
	v_ashrrev_i32_e32 v28, 3, v28
	v_ashrrev_i32_e32 v42, 4, v38
	v_mov_b64_e32 v[20:21], s[0:1]
	v_and_b32_e32 v34, -8, v18
	v_and_b32_e32 v36, -8, v28
	global_load_dwordx4 v[12:15], v[0:1], off
	global_load_dwordx4 v[8:11], v[0:1], off offset:64
	global_load_dwordx4 v[4:7], v[0:1], off offset:128
	s_nop 0
	global_load_dwordx4 v[0:3], v[0:1], off offset:192
	v_mad_i64_i32 v[16:17], s[12:13], v42, s88, v[20:21]
	v_ashrrev_i32_e32 v35, 31, v34
	v_mad_i64_i32 v[20:21], s[0:1], v33, s88, v[20:21]
	v_ashrrev_i32_e32 v37, 31, v36
	v_lshl_add_u64 v[16:17], v[16:17], 0, v[128:129]
	v_lshl_add_u64 v[18:19], v[34:35], 1, v[22:23]
	v_lshl_add_u64 v[20:21], v[20:21], 0, v[128:129]
	v_lshl_add_u64 v[22:23], v[36:37], 1, v[22:23]
	global_load_dwordx4 v[24:27], v[16:17], off offset:1024
	s_nop 0
	global_load_dwordx4 v[16:19], v[18:19], off offset:2048
	s_nop 0
	global_load_dwordx4 v[28:31], v[20:21], off offset:1024
	s_nop 0
	global_load_dwordx4 v[20:23], v[22:23], off offset:2048
	v_cndmask_b32_e32 v40, 0, v167, vcc
	v_add_f32_e32 v39, v39, v40
	v_exp_f32_e32 v39, v39
	s_mov_b32 s0, 0x3f2aaaab
	s_barrier
	v_ldexp_f32 v64, v39, s5
	v_sub_f32_e32 v44, 1.0, v64
	v_frexp_mant_f32_e32 v39, v44
	v_cmp_gt_f32_e32 vcc, s0, v39
	v_cmp_gt_i32_e64 s[0:1], s61, v38
	s_and_saveexec_b64 s[12:13], s[0:1]
	s_mov_b32 s18, 0x16100
	s_cbranch_execz .LBB0_344
	s_ashr_i32 s5, s4, 31
	s_lshl_b64 s[0:1], s[4:5], 16
	v_readlane_b32 s5, v252, 30
	s_add_u32 s0, s5, s0
	v_readlane_b32 s5, v252, 31
	v_ashrrev_i32_e32 v39, 31, v38
	s_addc_u32 s1, s5, s1
	v_lshl_add_u64 v[40:41], v[38:39], 4, s[0:1]
	v_lshlrev_b32_e32 v39, 2, v38
	s_mov_b64 s[14:15], 0

; DEV void sb_item(const Params& p, int item, unsigned char* smem) {
;   const int qb = 63 - (item & 63), h = (item >> 6) & 3, b = item >> 8;
;   const int tid = tidx(), w = tid >> 6, lane = tid & 63, fr = lane & 15, fq = lane >> 4;
;   u16* sP = (u16*)(smem + L_PW) + w * RW * VS;
;   int* flags = (int*)(smem + L_FLAG);
;   const u16* base = p.proj + (size_t)b * SEQ * DIN;
;   const int q0 = qb * QR + w * RW;
;   bf16x8 qf[MT][4];
;   load_qfrags(base + (size_t)q0 * DIN + C_SQ + h * 128, qf, fr, fq);
;   f32x4 o[MT][8];
;   float run[MT][4];
; #pragma unroll
;   for (int mt = 0; mt < MT; ++mt) {
; #pragma unroll
;     for (int nt = 0; nt < 8; ++nt) o[mt][nt] = (f32x4){0.f, 0.f, 0.f, 0.f};
; #pragma unroll
;     for (int j = 0; j < 4; ++j) run[mt][j] = 0.f;
;   }
;   const float scale = 0.08838834764831845f;
;   uint4 kq0, kq1, vq0, vq1;
;   {
;     const int kt0 = (qb * QR + QR - 1) / 64;
;     kv_load(base + (size_t)(kt0 * 64) * DIN + C_SK + h * 128, base + (size_t)(kt0 * 64) * DIN + C_SV + h * 128, kq0, kq1, vq0, vq1, tid);
;   }
;   __syncthreads();
;   int it = 0;
;     ...
;     u16* sK = (u16*)(smem + L_K + (it & 1) * KB_B); u16* sVt = (u16*)(smem + L_VT + (it & 1) * VB_B);
;     kv_store(kq0, kq1, vq0, vq1, sK, sVt, tid);
;     if (kt > 0) kv_load(base + (size_t)((kt - 1) * 64) * DIN + C_SK + h * 128, base + (size_t)((kt - 1) * 64) * DIN + C_SV + h * 128, kq0, kq1, vq0, vq1, tid);
;     __syncthreads();
.LBB0_422:
	s_ashr_i32 s92, s34, 8
	v_readfirstlane_b32 s0, v160
	s_andn2_b32 s0, s0, 63
	s_mul_i32 s1, s92, 0x5000000
	v_or_b32_e32 v51, s0, v161
	s_mul_hi_i32 s0, s92, 0x5000000
	s_add_u32 s12, s76, s1
	s_addc_u32 s13, s77, s0
	s_not_b32 s0, s34
	s_lshl_b32 s0, s0, 7
	s_and_b32 s14, s0, 0x1f80
	v_ashrrev_i32_e32 v49, 6, v51
	v_lshl_add_u32 v80, v49, 4, s14
	v_mov_b64_e32 v[0:1], s[12:13]
	v_mad_i64_i32 v[0:1], s[0:1], v80, s88, v[0:1]
	s_lshl_b32 s0, s34, 1
	s_lshr_b32 s35, s14, 6
	s_and_b32 s0, s0, 0x180
	s_or_b32 s4, s35, 1
	s_lshl_b32 s18, s0, 1
	s_mul_i32 s0, s4, 0xa0000
	s_add_u32 s0, s12, s0
	s_addc_u32 s1, s13, 0
	v_and_b32_e32 v92, 15, v51
	s_add_u32 s0, s0, s18
	v_mul_u32_u24_e32 v2, 0x1400, v92
	s_addc_u32 s1, s1, 0
	v_lshlrev_b32_e32 v6, 3, v51
	v_and_b32_e32 v48, 63, v51
	v_lshl_add_u64 v[0:1], v[0:1], 0, s[18:19]
	v_lshlrev_b32_e32 v128, 1, v2
	s_add_u32 s6, s0, 0x1400
	v_and_b32_e32 v6, 0x78, v6
	v_lshl_add_u64 v[0:1], v[0:1], 0, v[128:129]
	s_addc_u32 s7, s1, 0
	v_add_u32_e32 v10, 0x200, v51
	v_lshlrev_b32_e32 v128, 1, v6
	v_mul_u32_u24_e32 v6, 0x1400, v48
	v_ashrrev_i32_e32 v8, 3, v51
	v_ashrrev_i32_e32 v64, 4, v51
	v_mov_b64_e32 v[2:3], s[6:7]
	v_lshlrev_b32_e32 v82, 1, v6
	v_mov_b32_e32 v83, v129
	v_and_b32_e32 v84, -8, v8
	v_ashrrev_i32_e32 v65, 4, v10
	v_mad_i64_i32 v[4:5], s[6:7], v64, s88, v[2:3]
	v_lshl_add_u64 v[32:33], s[0:1], 0, v[82:83]
	v_ashrrev_i32_e32 v85, 31, v84
	v_mad_i64_i32 v[2:3], s[6:7], v65, s88, v[2:3]
	v_lshl_add_u64 v[4:5], v[4:5], 0, v[128:129]
	v_lshl_add_u64 v[6:7], v[32:33], 0, s[90:91]
	v_lshlrev_b64 v[34:35], 1, v[84:85]
	v_lshl_add_u64 v[2:3], v[2:3], 0, v[128:129]
	v_lshl_add_u64 v[8:9], v[6:7], 0, v[34:35]
	global_load_dwordx4 v[16:19], v[4:5], off
	global_load_dwordx4 v[20:23], v[2:3], off
	global_load_dwordx4 v[24:27], v[8:9], off
	v_ashrrev_i32_e32 v2, 3, v10
	v_and_b32_e32 v86, -8, v2
	v_ashrrev_i32_e32 v87, 31, v86
	v_lshlrev_b64 v[36:37], 1, v[86:87]
	v_lshl_add_u64 v[2:3], v[6:7], 0, v[36:37]
	global_load_dwordx4 v[28:31], v[2:3], off
	v_and_b32_e32 v38, 48, v51
	v_mov_b32_e32 v39, v129
	v_lshl_add_u64 v[4:5], v[0:1], 0, v[38:39]
	v_add_co_u32_e32 v0, vcc, s61, v4
	s_mov_b64 s[6:7], 0x1000
	s_nop 0
	v_addc_co_u32_e32 v1, vcc, 0, v5, vcc
	global_load_dwordx4 v[0:3], v[0:1], off
	v_lshl_add_u64 v[12:13], v[4:5], 0, s[6:7]
	global_load_dwordx4 v[4:7], v[12:13], off offset:64
	global_load_dwordx4 v[8:11], v[12:13], off offset:128
	s_nop 0
	global_load_dwordx4 v[12:15], v[12:13], off offset:192
	v_mul_lo_u32 v93, v64, s89
	s_add_u32 s0, s0, 0xfff61400
	v_lshlrev_b32_e32 v95, 1, v48
	v_mul_lo_u32 v96, v65, s89
	v_mul_lo_u32 v97, v84, s30
	v_mul_lo_u32 v98, v86, s30
	v_add_u32_e32 v40, v93, v128
	s_addc_u32 s1, s1, -1
	v_or_b32_e32 v39, v97, v95
	v_add_u32_e32 v41, v96, v128
	s_barrier
	v_mul_u32_u24_e32 v94, 0x88, v92
	v_lshl_add_u32 v50, v94, 1, v38
	v_bfe_u32 v99, v51, 4, 2
	v_lshl_or_b32 v100, v99, 2, v80
	v_mov_b32_e32 v75, 0
	s_waitcnt vmcnt(7)
	ds_write_b128 v40, v[16:19]
	s_waitcnt vmcnt(6)
	ds_write_b128 v41, v[20:23]
	s_waitcnt vmcnt(5)
	ds_write_b16 v39, v24 offset:34816
	ds_write_b16_d16_hi v39, v24 offset:34960
	ds_write_b16 v39, v25 offset:35104
	ds_write_b16_d16_hi v39, v25 offset:35248
	ds_write_b16 v39, v26 offset:35392
	ds_write_b16_d16_hi v39, v26 offset:35536
	ds_write_b16 v39, v27 offset:35680
	ds_write_b16_d16_hi v39, v27 offset:35824
	v_or_b32_e32 v16, v98, v95
	v_mov_b64_e32 v[24:25], s[0:1]
	s_waitcnt vmcnt(4)
	ds_write_b16 v16, v28 offset:34816
	ds_write_b16_d16_hi v16, v28 offset:34960
	ds_write_b16 v16, v29 offset:35104
	ds_write_b16_d16_hi v16, v29 offset:35248
	ds_write_b16 v16, v30 offset:35392
	ds_write_b16_d16_hi v16, v30 offset:35536
	ds_write_b16 v16, v31 offset:35680
	ds_write_b16_d16_hi v16, v31 offset:35824
	v_mad_i64_i32 v[16:17], s[0:1], v64, s88, v[24:25]
	s_mov_b32 s0, 0xfff61800
	s_mov_b32 s1, -1
	v_lshl_add_u64 v[28:29], v[32:33], 0, s[0:1]
	v_mad_i64_i32 v[24:25], s[0:1], v65, s88, v[24:25]
	v_lshl_add_u64 v[16:17], v[16:17], 0, v[128:129]
	v_lshl_add_u64 v[20:21], v[28:29], 0, v[34:35]
	v_lshl_add_u64 v[24:25], v[24:25], 0, v[128:129]
	v_lshl_add_u64 v[28:29], v[28:29], 0, v[36:37]
	global_load_dwordx4 v[16:19], v[16:17], off
	s_nop 0
	global_load_dwordx4 v[20:23], v[20:21], off
	s_nop 0
	global_load_dwordx4 v[24:27], v[24:25], off
	s_nop 0
	global_load_dwordx4 v[28:31], v[28:29], off
	s_waitcnt lgkmcnt(0)
	s_barrier
; DEV f32x4 mfma16(bf16x8 a, bf16x8 b, f32x4 c) { return __builtin_amdgcn_mfma_f32_16x16x32_bf16(a, b, c, 0, 0, 0); }
; DEV void qk_tile(const bf16x8 (&qf)[MT][4], const u16* sK, f32x4 (&s)[MT][4], int fr, int fq) {
; #pragma unroll
;   for (int mt = 0; mt < MT; ++mt)
; #pragma unroll
;     for (int jt = 0; jt < 4; ++jt) s[mt][jt] = (f32x4){0.f, 0.f, 0.f, 0.f};
; #pragma unroll
;   for (int ks = 0; ks < 4; ++ks) {
;     bf16x8 b[4];
; #pragma unroll
;     for (int jt = 0; jt < 4; ++jt) b[jt] = *(const bf16x8*)(sK + (jt * 16 + fr) * KS + ks * 32 + fq * 8);
; #pragma unroll
;     for (int jt = 0; jt < 4; ++jt)
; #pragma unroll
;       for (int mt = 0; mt < MT; ++mt) s[mt][jt] = mfma16(qf[mt][ks], b[jt], s[mt][jt]);
;   }
; DEV void sb_item(const Params& p, int item, unsigned char* smem) {
;     ...
;         const int tq = q0 + mt * 16 + fq * 4 + j;
;         float lk[4], lb[4], inc[4], tot[4];
; #pragma unroll
;         for (int jt = 0; jt < 4; ++jt) {
;           const int sk = kt * 64 + jt * 16 + fr;
;           const float z = s[mt][jt][j] * scale;
;           const float sp = fmaxf(z, 0.f) + __logf(1.0f + __expf(-fabsf(z)));
	ds_read_b128 v[32:35], v50
	ds_read_b128 v[52:55], v50 offset:64
	s_waitcnt vmcnt(7) lgkmcnt(1)
	v_mfma_f32_16x16x32_bf16 v[32:35], v[0:3], v[32:35], 0
	ds_read_b128 v[36:39], v50 offset:4352
	ds_read_b128 v[40:43], v50 offset:8704
	ds_read_b128 v[44:47], v50 offset:13056
	s_waitcnt vmcnt(6) lgkmcnt(3)
	v_mfma_f32_16x16x32_bf16 v[32:35], v[4:7], v[52:55], v[32:35]
	ds_read_b128 v[52:55], v50 offset:4416
	ds_read_b128 v[66:69], v50 offset:8896
	s_waitcnt lgkmcnt(4)
	v_mfma_f32_16x16x32_bf16 v[36:39], v[0:3], v[36:39], 0
	s_waitcnt lgkmcnt(1)
	v_mfma_f32_16x16x32_bf16 v[36:39], v[4:7], v[52:55], v[36:39]
	ds_read_b128 v[52:55], v50 offset:8768
	v_mfma_f32_16x16x32_bf16 v[40:43], v[0:3], v[40:43], 0
	s_waitcnt lgkmcnt(0)
	v_mfma_f32_16x16x32_bf16 v[40:43], v[4:7], v[52:55], v[40:43]
	ds_read_b128 v[52:55], v50 offset:13120
	v_mfma_f32_16x16x32_bf16 v[44:47], v[0:3], v[44:47], 0
	s_waitcnt lgkmcnt(0)
	v_mfma_f32_16x16x32_bf16 v[44:47], v[4:7], v[52:55], v[44:47]
	ds_read_b128 v[52:55], v50 offset:128
	s_waitcnt vmcnt(5) lgkmcnt(0)
	v_mfma_f32_16x16x32_bf16 v[32:35], v[8:11], v[52:55], v[32:35]
	ds_read_b128 v[52:55], v50 offset:4480
	s_waitcnt lgkmcnt(0)
	v_mfma_f32_16x16x32_bf16 v[36:39], v[8:11], v[52:55], v[36:39]
	ds_read_b128 v[52:55], v50 offset:8832
	s_waitcnt lgkmcnt(0)
	v_mfma_f32_16x16x32_bf16 v[56:59], v[8:11], v[52:55], v[40:43]
	s_nop 2
	ds_read_b128 v[40:43], v50 offset:13184
	s_waitcnt lgkmcnt(0)
	v_mfma_f32_16x16x32_bf16 v[60:63], v[8:11], v[40:43], v[44:47]
	ds_read_b128 v[40:43], v50 offset:192
	s_waitcnt vmcnt(4) lgkmcnt(0)
	v_mfma_f32_16x16x32_bf16 v[44:47], v[12:15], v[40:43], v[32:35]
	s_nop 2
	ds_read_b128 v[32:35], v50 offset:4544
	s_waitcnt lgkmcnt(0)
	v_mfma_f32_16x16x32_bf16 v[40:43], v[12:15], v[32:35], v[36:39]
	s_nop 1
	v_mul_f32_e32 v54, 0x3db504f3, v44
	v_mul_f32_e64 v32, |v54|, s31
	v_exp_f32_e32 v44, v32
	v_max_f32_e32 v52, 0, v54
	v_mfma_f32_16x16x32_bf16 v[36:39], v[12:15], v[66:69], v[56:59]
	ds_read_b128 v[32:35], v50 offset:13248
	v_add_f32_e32 v44, 1.0, v44
	v_cmp_gt_f32_e32 vcc, s84, v44
	v_mul_f32_e32 v59, 0x3db504f3, v40
	v_mul_f32_e64 v40, |v59|, s31
	v_cndmask_b32_e64 v51, 0, 32, vcc
	v_ldexp_f32 v44, v44, v51
	v_log_f32_e32 v44, v44
	v_lshl_or_b32 v51, s4, 6, v92
	s_waitcnt lgkmcnt(0)
; DEV void sb_item(const Params& p, int item, unsigned char* smem) {
;     ...
;         const int tq = q0 + mt * 16 + fq * 4 + j;
;         float lk[4], lb[4], inc[4], tot[4];
; #pragma unroll
;         for (int jt = 0; jt < 4; ++jt) {
;           const int sk = kt * 64 + jt * 16 + fr;
;           const float z = s[mt][jt][j] * scale;
;           const float sp = fmaxf(z, 0.f) + __logf(1.0f + __expf(-fabsf(z)));
;           lk[jt] = (sk < tq) ? -sp : 0.f;
;           lb[jt] = z - sp;
;           float x = lk[jt];
;           x += dpp_f<0x101>(x); x += dpp_f<0x102>(x); x += dpp_f<0x104>(x); x += dpp_f<0x108>(x);
;           inc[jt] = x;
;           tot[jt] = grp16_sum_fast(lk[jt]);
;         }
;         float after = 0.f;
; #pragma unroll
;     ...
;           const int sk = kt * 64 + jt * 16 + fr;
;           const float e = lb[jt] + (inc[jt] - lk[jt]) + after + run[mt][j];
;           const float a = (sk < tq) ? __expf(e) : 0.f;
;           sP[(mt * 16 + fq * 4 + j) * VS + jt * 16 + fr] = f2bf(a);
;           after += tot[jt];
;         }
	v_mfma_f32_16x16x32_bf16 v[32:35], v[12:15], v[32:35], v[60:63]
	v_max_f32_e32 v55, 0, v59
	v_mul_f32_e32 v53, 0x3f317217, v44
	v_fma_f32 v53, v44, s29, -v53
	v_fmac_f32_e32 v53, 0x3377d1cf, v44
	v_fmac_f32_e32 v53, 0x3f317217, v44
	v_cmp_lt_f32_e64 s[0:1], |v44|, s36
	v_mul_f32_e32 v63, 0x3db504f3, v36
	v_mul_f32_e64 v36, |v63|, s31
	v_cndmask_b32_e64 v44, v44, v53, s[0:1]
	v_cndmask_b32_e32 v53, 0, v171, vcc
	v_sub_f32_e32 v44, v44, v53
	v_add_f32_e32 v56, v52, v44
	v_cmp_lt_i32_e32 vcc, v51, v100
	v_exp_f32_e32 v36, v36
	s_nop 0
	v_cndmask_b32_e64 v44, 0, -v56, vcc
	v_add_f32_e32 v36, 1.0, v36
	s_nop 0
	v_add_f32_dpp v52, v44, v44 row_shl:1 row_mask:0xf bank_mask:0xf bound_ctrl:1
	s_nop 1
	v_add_f32_dpp v52, v52, v52 row_shl:2 row_mask:0xf bank_mask:0xf bound_ctrl:1
	s_nop 1
	v_add_f32_dpp v57, v52, v52 row_shl:4 row_mask:0xf bank_mask:0xf bound_ctrl:1
	v_exp_f32_e32 v52, v40
	v_add_f32_dpp v40, v44, v44 row_ror:8 row_mask:0xf bank_mask:0xf bound_ctrl:1
	v_mov_b32_dpp v58, v57 row_shl:8 row_mask:0xf bank_mask:0xf bound_ctrl:1
	v_add_f32_e32 v44, 1.0, v52
	v_cmp_gt_f32_e64 s[0:1], s84, v44
	v_add_f32_dpp v40, v40, v40 row_ror:4 row_mask:0xf bank_mask:0xf bound_ctrl:1
	s_nop 0
	v_cndmask_b32_e64 v52, 0, 32, s[0:1]
	v_ldexp_f32 v44, v44, v52
	v_log_f32_e32 v53, v44
	v_or_b32_e32 v52, 16, v51
	v_add_f32_dpp v40, v40, v40 row_ror:2 row_mask:0xf bank_mask:0xf bound_ctrl:1
	v_mul_f32_e32 v60, 0x3f317217, v53
	v_fma_f32 v60, v53, s29, -v60
	v_fmac_f32_e32 v60, 0x3377d1cf, v53
	v_fmac_f32_e32 v60, 0x3f317217, v53
	v_cmp_lt_f32_e64 s[4:5], |v53|, s36
	v_mov_b32_dpp v44, v40 row_ror:1 row_mask:0xf bank_mask:0xf bound_ctrl:1
	s_nop 0
	v_cndmask_b32_e64 v53, v53, v60, s[4:5]
	v_cndmask_b32_e64 v60, 0, v171, s[0:1]
	v_sub_f32_e32 v53, v53, v60
	v_add_f32_e32 v60, v55, v53
	v_cmp_lt_i32_e64 s[0:1], v52, v100
	v_cmp_gt_f32_e64 s[4:5], s84, v36
	s_nop 0
	v_cndmask_b32_e64 v53, 0, -v60, s[0:1]
	s_nop 1
	v_add_f32_dpp v55, v53, v53 row_shl:1 row_mask:0xf bank_mask:0xf bound_ctrl:1
	v_add_f32_dpp v53, v53, v53 row_ror:8 row_mask:0xf bank_mask:0xf bound_ctrl:1
	s_nop 0
	v_add_f32_dpp v55, v55, v55 row_shl:2 row_mask:0xf bank_mask:0xf bound_ctrl:1
	v_add_f32_dpp v53, v53, v53 row_ror:4 row_mask:0xf bank_mask:0xf bound_ctrl:1
	s_nop 0
	v_add_f32_dpp v61, v55, v55 row_shl:4 row_mask:0xf bank_mask:0xf bound_ctrl:1
	v_add_f32_dpp v66, v53, v53 row_ror:2 row_mask:0xf bank_mask:0xf bound_ctrl:1
	v_cndmask_b32_e64 v53, 0, 32, s[4:5]
	v_ldexp_f32 v36, v36, v53
	v_log_f32_e32 v53, v36
	v_or_b32_e32 v36, 32, v51
	v_max_f32_e32 v55, 0, v63
	v_mov_b32_dpp v62, v61 row_shl:8 row_mask:0xf bank_mask:0xf bound_ctrl:1
	v_mul_f32_e32 v68, 0x3f317217, v53
	v_fma_f32 v68, v53, s29, -v68
	v_fmac_f32_e32 v68, 0x3377d1cf, v53
	v_fmac_f32_e32 v68, 0x3f317217, v53
	v_cmp_lt_f32_e64 s[6:7], |v53|, s36
	v_mov_b32_dpp v67, v66 row_ror:1 row_mask:0xf bank_mask:0xf bound_ctrl:1
	s_nop 0
	v_cndmask_b32_e64 v53, v53, v68, s[6:7]
	v_cndmask_b32_e64 v68, 0, v171, s[4:5]
	v_sub_f32_e32 v53, v53, v68
	v_add_f32_e32 v68, v55, v53
	v_cmp_lt_i32_e64 s[4:5], v36, v100
	s_nop 1
	v_cndmask_b32_e64 v55, 0, -v68, s[4:5]
	s_nop 1
	v_add_f32_dpp v53, v55, v55 row_shl:1 row_mask:0xf bank_mask:0xf bound_ctrl:1
	v_add_f32_dpp v55, v55, v55 row_ror:8 row_mask:0xf bank_mask:0xf bound_ctrl:1
	s_nop 0
	v_add_f32_dpp v53, v53, v53 row_shl:2 row_mask:0xf bank_mask:0xf bound_ctrl:1
	v_add_f32_dpp v55, v55, v55 row_ror:4 row_mask:0xf bank_mask:0xf bound_ctrl:1
	s_nop 0
	v_add_f32_dpp v69, v53, v53 row_shl:4 row_mask:0xf bank_mask:0xf bound_ctrl:1
	v_mul_f32_e32 v53, 0x3db504f3, v32
	v_mul_f32_e64 v32, |v53|, s31
	v_exp_f32_e32 v32, v32
	v_add_f32_dpp v71, v55, v55 row_ror:2 row_mask:0xf bank_mask:0xf bound_ctrl:1
	v_max_f32_e32 v73, 0, v53
	v_mov_b32_dpp v70, v69 row_shl:8 row_mask:0xf bank_mask:0xf bound_ctrl:1
	v_add_f32_e32 v32, 1.0, v32
	v_cmp_gt_f32_e64 s[6:7], s84, v32
	v_mov_b32_dpp v72, v71 row_ror:1 row_mask:0xf bank_mask:0xf bound_ctrl:1
	s_nop 0
	v_cndmask_b32_e64 v55, 0, 32, s[6:7]
	v_ldexp_f32 v32, v32, v55
	v_log_f32_e32 v55, v32
	v_or_b32_e32 v32, 48, v51
	v_mul_f32_e32 v74, 0x3f317217, v55
	v_fma_f32 v74, v55, s29, -v74
	v_fmac_f32_e32 v74, 0x3377d1cf, v55
	v_fmac_f32_e32 v74, 0x3f317217, v55
	v_cmp_lt_f32_e64 s[10:11], |v55|, s36
	s_nop 1
	v_cndmask_b32_e64 v55, v55, v74, s[10:11]
	v_cndmask_b32_e64 v74, 0, v171, s[6:7]
	v_sub_f32_e32 v55, v55, v74
	v_add_f32_e32 v76, v73, v55
	v_cmp_lt_i32_e64 s[6:7], v32, v100
	s_nop 1
	v_cndmask_b32_e64 v55, 0, -v76, s[6:7]
	s_nop 1
	v_add_f32_dpp v73, v55, v55 row_shl:1 row_mask:0xf bank_mask:0xf bound_ctrl:1
	v_add_f32_dpp v55, v55, v55 row_ror:8 row_mask:0xf bank_mask:0xf bound_ctrl:1
	s_nop 0
	v_add_f32_dpp v73, v73, v73 row_shl:2 row_mask:0xf bank_mask:0xf bound_ctrl:1
	v_add_f32_dpp v55, v55, v55 row_ror:4 row_mask:0xf bank_mask:0xf bound_ctrl:1
	s_nop 0
	v_add_f32_dpp v77, v73, v73 row_shl:4 row_mask:0xf bank_mask:0xf bound_ctrl:1
	v_add_f32_dpp v73, v55, v55 row_ror:2 row_mask:0xf bank_mask:0xf bound_ctrl:1
	v_mov_b32_e32 v55, 0
	v_mov_b32_dpp v78, v77 row_shl:8 row_mask:0xf bank_mask:0xf bound_ctrl:1
	v_mov_b32_dpp v74, v73 row_ror:1 row_mask:0xf bank_mask:0xf bound_ctrl:1
	s_and_saveexec_b64 s[10:11], s[6:7]
	s_cbranch_execz .LBB0_424
	v_add_f32_e32 v75, v77, v78
	v_sub_f32_e32 v53, v53, v76
	v_add_f32_e32 v75, v76, v75
	v_add_f32_e32 v53, v53, v75
	v_add_f32_e32 v53, 0, v53
	v_mul_f32_e32 v53, 0x3fb8aa3b, v53
	v_exp_f32_e32 v53, v53
	s_nop 0
	v_cvt_pk_bf16_f32 v75, v53, s0

; DEV void swa_item(const Params& p, int l, int item, unsigned char* smem) {
;   const int qh = item & 7, n = (item >> 3) & 63, b = item >> 9, kvh = qh >> 2;
;   const int tid = tidx(), w = tid >> 6, lane = tid & 63, fr = lane & 15, fq = lane >> 4;
;   u16* sP = (u16*)(smem + L_PW) + w * RW * VS;
;   const u16* base = p.proj + (size_t)b * SEQ * DIN;
;   const int q0 = n * QR + w * RW;
;   bf16x8 qf[MT][4];
;   load_qfrags(base + (size_t)q0 * DIN + C_AQ + qh * 128, qf, fr, fq);
;   const float sink = p.sinks[l * 8 + qh];
;   const float slope = exp2f(-(float)(qh + 1));
;   const float scale = 0.08838834764831845f;
;   f32x4 o[MT][8];
;   float m[MT][4], lsum[MT][4];
; #pragma unroll
;   for (int mt = 0; mt < MT; ++mt) {
; #pragma unroll
;     for (int nt = 0; nt < 8; ++nt) o[mt][nt] = (f32x4){0.f, 0.f, 0.f, 0.f};
; #pragma unroll
;     for (int j = 0; j < 4; ++j) { m[mt][j] = sink; lsum[mt][j] = 1.0f; }
;   }
;   constexpr int NKT = (QR + 128) / 64;
;   const int ktf = (n == 0) ? 2 : 0;
;   uint4 kq0, kq1, vq0, vq1;
;   {
;     const int k0 = n * QR - 128 + ktf * 64;
;     kv_load(base + (size_t)k0 * DIN + C_AK + kvh * 128, base + (size_t)k0 * DIN + C_AV + kvh * 128, kq0, kq1, vq0, vq1, tid);
;   }
;   __syncthreads();
;   int it = 0;
;   for (int kt = ktf; kt < NKT; ++kt, ++it) {
;     const int key0 = n * QR - 128 + kt * 64;
;     u16* sK = (u16*)(smem + L_K + (it & 1) * KB_B); u16* sVt = (u16*)(smem + L_VT + (it & 1) * VB_B);
;     kv_store(kq0, kq1, vq0, vq1, sK, sVt, tid);
;     if (kt + 1 < NKT) kv_load(base + (size_t)(key0 + 64) * DIN + C_AK + kvh * 128, base + (size_t)(key0 + 64) * DIN + C_AV + kvh * 128, kq0, kq1, vq0, vq1, tid);
.LBB0_475:
	v_readfirstlane_b32 s1, v160
	s_and_b32 s0, s7, 4
	s_ashr_i32 s2, s10, 9
	s_andn2_b32 s1, s1, 63
	s_lshl_b32 s0, s0, 6
	s_and_b32 s13, s10, 7
	s_bfe_u32 s16, s10, 0x60003
	v_or_b32_e32 v17, s1, v161
	s_ashr_i32 s3, s2, 31
	s_mul_i32 s28, s2, 0x5000000
	s_mul_hi_i32 s1, s2, 0x5000000
	v_ashrrev_i32_e32 v0, 2, v17
	s_add_u32 s14, s76, s28
	v_and_b32_e32 v48, -16, v0
	s_addc_u32 s15, s77, s1
	s_lshl_b32 s17, s16, 7
	v_and_b32_e32 v91, 15, v17
	v_add_u32_e32 v80, s17, v48
	v_mov_b64_e32 v[0:1], s[14:15]
	v_mad_i64_i32 v[0:1], s[4:5], v80, s88, v[0:1]
	s_lshl_b32 s18, s13, 8
	v_mul_u32_u24_e32 v2, 0x1400, v91
	v_bfe_u32 v102, v17, 4, 2
	v_lshl_add_u64 v[0:1], v[0:1], 0, s[18:19]
	v_lshlrev_b32_e32 v128, 1, v2
	v_lshl_add_u64 v[0:1], v[0:1], 0, v[128:129]
	v_lshlrev_b32_e32 v128, 4, v102
	v_lshl_add_u64 v[0:1], v[0:1], 0, v[128:129]
	s_mov_b64 s[4:5], 0x1c00
	v_lshl_add_u64 v[12:13], v[0:1], 0, s[4:5]
	s_or_b32 s4, s13, s6
	v_add_co_u32_e32 v8, vcc, s61, v0
	s_lshl_b32 s4, s4, 2
	v_readlane_b32 s44, v253, 6
	s_lshl_b32 s11, s13, 7
	v_addc_co_u32_e32 v9, vcc, 0, v1, vcc
	v_mov_b32_e32 v18, s4
	v_readlane_b32 s52, v253, 14
	v_readlane_b32 s53, v253, 15
	s_add_i32 s13, s13, 1
	global_load_dwordx4 v[0:3], v[12:13], off offset:64
	global_load_dwordx4 v[4:7], v[12:13], off offset:128
	s_nop 0
	global_load_dwordx4 v[8:11], v[8:9], off offset:3072
	s_nop 0
	global_load_dwordx4 v[12:15], v[12:13], off offset:192
	s_mov_b32 s4, 0x42fc0000
	global_load_dword v114, v18, s[52:53]
	v_cvt_f32_ubyte0_e32 v18, s13
	v_mul_lo_u32 v16, v48, s30
	v_cmp_lt_f32_e32 vcc, s4, v18
	v_add_u32_e32 v50, 0x11800, v16
	s_and_b64 s[4:5], vcc, exec
	v_cndmask_b32_e32 v16, 0, v167, vcc
	v_sub_f32_e32 v16, v16, v18
	v_exp_f32_e32 v18, v16
	s_cselect_b32 s4, 0xffffffc0, 0
	s_cmp_eq_u32 s16, 0
	s_cselect_b32 s13, 2, 0
	s_lshl_b32 s18, s13, 6
	s_add_i32 s41, s17, s18
	v_ldexp_f32 v85, v18, s4
	s_mul_i32 s4, s41, 0x1400
	s_add_i32 s4, s4, 0xfff60000
	s_ashr_i32 s5, s4, 31
	s_lshl_b64 s[4:5], s[4:5], 1
	s_add_u32 s14, s14, s4
	s_addc_u32 s15, s15, s5
	s_lshl_b32 s16, s10, 6
	s_and_b32 s16, s16, 0x100
	s_add_u32 s14, s14, s16
	s_waitcnt vmcnt(39)
	v_lshlrev_b32_e32 v22, 3, v17
	s_addc_u32 s15, s15, 0
	v_add_u32_e32 v32, 0x200, v17
	v_ashrrev_i32_e32 v51, 4, v17
	v_and_b32_e32 v22, 0x78, v22
	v_and_b32_e32 v103, 63, v17
	v_ashrrev_i32_e32 v17, 3, v17
	s_add_u32 s16, s14, 0x2400
	v_lshlrev_b32_e32 v86, 1, v22
	v_mul_u32_u24_e32 v22, 0x1400, v103
	v_and_b32_e32 v38, -8, v17
	v_ashrrev_i32_e32 v17, 4, v32
	v_ashrrev_i32_e32 v32, 3, v32
	s_addc_u32 s17, s15, 0
	v_lshlrev_b32_e32 v36, 1, v22
	v_mov_b32_e32 v37, v129
	v_and_b32_e32 v44, -8, v32
	s_waitcnt vmcnt(37)
	v_mov_b64_e32 v[28:29], s[16:17]
	v_lshl_add_u64 v[22:23], s[14:15], 0, v[36:37]
	s_mov_b64 s[14:15], 0x2600
	v_ashrrev_i32_e32 v39, 31, v38
	v_ashrrev_i32_e32 v45, 31, v44
	v_mad_i64_i32 v[20:21], s[16:17], v51, s88, v[28:29]
	v_mov_b32_e32 v87, v129
	v_lshl_add_u64 v[30:31], v[22:23], 0, s[14:15]
	v_lshlrev_b64 v[40:41], 1, v[38:39]
	v_mad_i64_i32 v[28:29], s[14:15], v17, s88, v[28:29]
	v_lshlrev_b64 v[46:47], 1, v[44:45]
	v_lshl_add_u64 v[20:21], v[20:21], 0, v[86:87]
	v_lshl_add_u64 v[24:25], v[30:31], 0, v[40:41]
	v_lshl_add_u64 v[28:29], v[28:29], 0, v[86:87]
	v_lshl_add_u64 v[32:33], v[30:31], 0, v[46:47]
	global_load_dwordx4 v[20:23], v[20:21], off
	s_nop 0
	global_load_dwordx4 v[24:27], v[24:25], off
	s_nop 0
	global_load_dwordx4 v[28:31], v[28:29], off
	s_nop 0
	global_load_dwordx4 v[32:35], v[32:33], off
	v_mul_lo_u32 v106, v38, s30
	v_lshlrev_b32_e32 v38, 2, v102
	v_or_b32_e32 v39, v80, v38
	v_or_b32_e32 v38, v48, v38
	v_mad_i64_i32 v[18:19], s[34:35], v51, s88, 0
	v_sub_u32_e32 v38, v38, v91
	v_subrev_u32_e32 v110, s18, v38
	v_mad_i64_i32 v[18:19], s[16:17], s2, v173, v[18:19]
	v_lshlrev_b32_e32 v38, 4, v91
	v_mad_i64_i32 v[42:43], s[14:15], v17, s88, 0
	v_or3_b32 v18, v18, s0, v38
	v_lshl_add_u64 v[94:95], s[76:77], 0, v[18:19]
	v_mad_i64_i32 v[18:19], s[16:17], s2, v173, v[42:43]
	v_or3_b32 v18, v18, s0, v38
	s_or_b32 s0, s28, s0
	v_lshl_add_u64 v[96:97], s[76:77], 0, v[18:19]
	v_lshl_add_u64 v[18:19], s[0:1], 0, v[40:41]
	v_lshl_add_u64 v[18:19], v[18:19], 0, v[36:37]
	v_mul_lo_u32 v107, v44, s30
	v_lshl_or_b32 v44, v91, 1, v50
	v_or_b32_e32 v45, v50, v128
	v_mul_u32_u24_e32 v108, 0x48, v91
	v_or_b32_e32 v50, 1, v39
	v_lshl_add_u64 v[98:99], s[76:77], 0, v[18:19]
	v_lshl_add_u64 v[18:19], s[0:1], 0, v[46:47]
	v_lshlrev_b32_e32 v49, 3, v102
	v_mov_b32_e32 v16, 0
	v_mul_lo_u32 v105, v17, s89
	v_mul_u32_u24_e32 v17, 0x88, v91
	v_lshl_add_u32 v109, v108, 1, v45
	v_sub_u32_e32 v87, v39, v91
	v_mul_u32_u24_e32 v45, 0x240, v102
	v_sub_u32_e32 v88, v50, v91
	v_or_b32_e32 v50, 2, v39
	v_or_b32_e32 v39, 3, v39
	v_lshl_add_u64 v[18:19], v[18:19], 0, v[36:37]
	v_mov_b32_e32 v82, 1.0
	v_ashrrev_i32_e32 v81, 31, v80
	s_mov_b32 s12, 0
	v_mul_lo_u32 v104, v51, s89
	v_sub_u32_e32 v89, v50, v91
	v_sub_u32_e32 v90, v39, v91
	s_or_b32 s14, s18, 0xffffff40
	s_sub_i32 s15, 0x50, s41
	v_lshl_add_u64 v[100:101], s[76:77], 0, v[18:19]
	v_lshlrev_b32_e32 v111, 1, v49
	v_lshlrev_b32_e32 v112, 1, v17
	v_add_u32_e32 v113, v44, v45
	s_waitcnt vmcnt(4)
	v_mov_b32_e32 v116, v114
	v_mov_b32_e32 v118, v114
	v_mov_b32_e32 v117, v114
	s_mov_b32 s16, 0
	v_mov_b32_e32 v17, v16
	v_mov_b32_e32 v18, v16
	v_mov_b32_e32 v19, v16
	v_mov_b32_e32 v36, v16
	v_mov_b32_e32 v37, v16
	v_mov_b32_e32 v38, v16
	v_mov_b32_e32 v39, v16
	v_mov_b32_e32 v40, v16
	v_mov_b32_e32 v41, v16
	v_mov_b32_e32 v42, v16
	v_mov_b32_e32 v43, v16
	v_mov_b32_e32 v44, v16
	v_mov_b32_e32 v45, v16
	v_mov_b32_e32 v46, v16
	v_mov_b32_e32 v47, v16
	v_mov_b32_e32 v48, v16
	v_mov_b32_e32 v49, v16
	v_mov_b32_e32 v50, v16
	v_mov_b32_e32 v51, v16
	v_mov_b32_e32 v52, v16
	v_mov_b32_e32 v53, v16
	v_mov_b32_e32 v54, v16
	v_mov_b32_e32 v55, v16
	v_mov_b32_e32 v56, v16
	v_mov_b32_e32 v57, v16
	v_mov_b32_e32 v58, v16
	v_mov_b32_e32 v59, v16
	v_mov_b32_e32 v60, v16
	v_mov_b32_e32 v61, v16
	v_mov_b32_e32 v62, v16
	v_mov_b32_e32 v63, v16
	v_mov_b32_e32 v83, v82
	v_mov_b32_e32 v92, v82
	v_mov_b32_e32 v93, v82
	v_readlane_b32 s45, v253, 7
	v_readlane_b32 s46, v253, 8
	v_readlane_b32 s47, v253, 9
	v_readlane_b32 s48, v253, 10
	v_readlane_b32 s49, v253, 11
	v_readlane_b32 s50, v253, 12
	v_readlane_b32 s51, v253, 13
	v_readlane_b32 s54, v253, 16
	v_readlane_b32 s55, v253, 17
	v_readlane_b32 s56, v253, 18
	v_readlane_b32 s57, v253, 19
	v_readlane_b32 s58, v253, 20
	v_readlane_b32 s59, v253, 21
	s_waitcnt lgkmcnt(0)
	s_barrier
	s_branch .LBB0_477

; DEV float log_gamma(int h) { return log1pf(-exp2f(-5.0f - (float)h)); }
; DEV void ret_state_item(const Params& p, int item, unsigned char* smem) {
;   const int h = item & 3, n = (item >> 2) & 63, b = item >> 8;
;   const int tid = tidx(), w = tid >> 6, lane = tid & 63, fr = lane & 15, fq = lane >> 4;
;   u16* sKz = (u16*)smem;
;   u16* sVt = (u16*)(smem + 128 * VS * 2);
;   const u16* base = p.proj + ((size_t)b * SEQ + n * 128) * DIN;
;   const float lg = log_gamma(h);
;   f32x4 acc[MTS][8];
; #pragma unroll
;   for (int mt = 0; mt < MTS; ++mt)
; #pragma unroll
;     for (int nt = 0; nt < 8; ++nt) acc[mt][nt] = (f32x4){0.f, 0.f, 0.f, 0.f};
; #pragma unroll 1
.LBB0_489:
	v_readfirstlane_b32 s1, v160
	s_ashr_i32 s0, s2, 8
	s_andn2_b32 s1, s1, 63
	v_or_b32_e32 v33, s1, v161
	s_ashr_i32 s1, s0, 31
	s_lshl_b32 s3, s2, 5
	s_and_b32 s10, s2, 3
	s_lshl_b64 s[0:1], s[0:1], 13
	s_and_b32 s3, s3, 0x1f80
	s_or_b32 s0, s0, s3
	v_cvt_f32_ubyte0_e32 v0, s10
	s_mul_hi_u32 s3, s0, 0x2800
	s_mul_i32 s5, s0, 0x2800
	v_sub_f32_e32 v1, 0xc0a00000, v0
	s_mov_b32 s0, 0xc2fc0000
	v_cmp_gt_f32_e32 vcc, s0, v1
	s_mulk_i32 s1, 0x2800
	s_add_i32 s4, s3, s1
	v_cndmask_b32_e32 v2, 0, v167, vcc
	v_add_f32_e32 v1, v1, v2
	v_exp_f32_e32 v1, v1
	s_and_b64 s[0:1], vcc, exec
	s_cselect_b32 s0, 0xffffffc0, 0
	v_ldexp_f32 v1, v1, s0
	v_sub_f32_e32 v4, 1.0, v1
	v_add_f32_e32 v2, -1.0, v4
	v_sub_f32_e32 v3, v2, v4
	v_add_f32_e32 v3, 1.0, v3
	v_sub_f32_e64 v2, -v1, v2
	v_add_f32_e32 v5, v2, v3
	v_frexp_mant_f32_e32 v6, v4
	v_cvt_f64_f32_e32 v[2:3], v4
	s_mov_b32 s0, 0x3f2aaaab
	v_frexp_exp_i32_f64_e32 v2, v[2:3]
	v_cmp_gt_f32_e32 vcc, s0, v6
	s_mov_b32 s0, 0x3f317218
	s_add_u32 s11, s76, s5
	v_subbrev_co_u32_e32 v2, vcc, 0, v2, vcc
	v_sub_u32_e32 v3, 0, v2
	v_ldexp_f32 v4, v4, v3
	v_ldexp_f32 v3, v5, v3
	v_add_f32_e32 v5, -1.0, v4
	v_add_f32_e32 v8, 1.0, v4
	v_add_f32_e32 v6, 1.0, v5
	v_add_f32_e32 v9, -1.0, v8
	v_sub_f32_e32 v6, v4, v6
	v_sub_f32_e32 v4, v4, v9
	v_add_f32_e32 v6, v3, v6
	v_add_f32_e32 v3, v3, v4
	v_add_f32_e32 v4, v8, v3
	v_rcp_f32_e32 v9, v4
	v_add_f32_e32 v7, v5, v6
	v_sub_f32_e32 v5, v7, v5
	v_sub_f32_e32 v5, v6, v5
	v_sub_f32_e32 v6, v4, v8
	v_sub_f32_e32 v3, v3, v6
	v_mul_f32_e32 v6, v7, v9
	v_mul_f32_e32 v8, v4, v6
	v_fma_f32 v10, v6, v4, -v8
	v_fmac_f32_e32 v10, v6, v3
	v_add_f32_e32 v11, v8, v10
	v_sub_f32_e32 v12, v7, v11
	v_sub_f32_e32 v7, v7, v12
	v_sub_f32_e32 v8, v11, v8
	v_sub_f32_e32 v7, v7, v11
	v_add_f32_e32 v5, v5, v7
	v_sub_f32_e32 v7, v8, v10
	v_add_f32_e32 v5, v7, v5
	v_add_f32_e32 v7, v12, v5
	v_mul_f32_e32 v8, v9, v7
	v_mul_f32_e32 v10, v4, v8
	v_fma_f32 v4, v8, v4, -v10
	v_fmac_f32_e32 v4, v8, v3
	v_sub_f32_e32 v3, v12, v7
	v_add_f32_e32 v3, v5, v3
	v_add_f32_e32 v5, v10, v4
	v_sub_f32_e32 v11, v7, v5
	v_sub_f32_e32 v7, v7, v11
	v_sub_f32_e32 v10, v5, v10
	v_sub_f32_e32 v5, v7, v5
	v_add_f32_e32 v3, v3, v5
	v_sub_f32_e32 v4, v10, v4
	v_cvt_f32_i32_e32 v2, v2
	v_add_f32_e32 v3, v4, v3
	v_add_f32_e32 v4, v6, v8
	v_add_f32_e32 v3, v11, v3
	v_sub_f32_e32 v5, v4, v6
	v_mul_f32_e32 v3, v9, v3
	v_sub_f32_e32 v5, v8, v5
	v_add_f32_e32 v3, v5, v3
	v_mul_f32_e32 v8, 0x3f317218, v2
	v_add_f32_e32 v5, v4, v3
	v_fma_f32 v9, v2, s0, -v8
	v_mul_f32_e32 v6, v5, v5
	v_fmac_f32_e32 v9, 0xb102e308, v2
	v_sub_f32_e32 v2, v5, v4
	v_fmamk_f32 v7, v6, 0x3e9b6dac, v164
	v_sub_f32_e32 v2, v3, v2
	v_add_f32_e32 v3, v8, v9
	v_fmaak_f32 v7, v6, v7, 0x3f2aaada
	v_sub_f32_e32 v4, v3, v8
	v_ldexp_f32 v8, v5, 1
	v_mul_f32_e32 v5, v5, v6
	v_mul_f32_e32 v5, v5, v7
	v_add_f32_e32 v6, v8, v5
	v_sub_f32_e32 v7, v6, v8
	v_ldexp_f32 v2, v2, 1
	v_sub_f32_e32 v5, v5, v7
	v_add_f32_e32 v2, v2, v5
	v_add_f32_e32 v5, v6, v2
	v_sub_f32_e32 v6, v5, v6
	v_sub_f32_e32 v2, v2, v6
	v_add_f32_e32 v6, v3, v5
	v_sub_f32_e32 v7, v6, v3
	v_sub_f32_e32 v8, v6, v7
	v_sub_f32_e32 v4, v9, v4
	v_sub_f32_e32 v3, v3, v8
	v_sub_f32_e32 v5, v5, v7
	v_add_f32_e32 v3, v5, v3
	v_add_f32_e32 v5, v4, v2
	v_sub_f32_e32 v7, v5, v4
	v_sub_f32_e32 v8, v5, v7
	v_sub_f32_e32 v4, v4, v8
	v_sub_f32_e32 v2, v2, v7
	v_add_f32_e32 v3, v5, v3
	v_add_f32_e32 v2, v2, v4
	v_add_f32_e32 v4, v6, v3
	v_sub_f32_e32 v5, v4, v6
	v_sub_f32_e32 v3, v3, v5
	v_add_f32_e32 v2, v2, v3
	v_add_f32_e32 v2, v4, v2
	v_max_i32_e32 v4, 0x200, v33
	v_cmp_nlt_f32_e32 vcc, 1.0, v1
	v_sub_u32_e32 v4, v4, v33
	s_mov_b32 s0, 0x33800000
	v_cndmask_b32_e32 v2, v168, v2, vcc
	v_cmp_neq_f32_e32 vcc, 1.0, v1
	v_add_u32_e32 v4, 0x1ff, v4
	v_and_b32_e32 v5, 0x200, v4
	v_cndmask_b32_e32 v2, v169, v2, vcc
	v_cmp_gt_f32_e32 vcc, s0, v1
	s_addc_u32 s12, s77, s4
	v_cmp_eq_u32_e64 s[4:5], 0, v5
	v_cndmask_b32_e64 v40, v2, -v1, vcc
	v_ashrrev_i32_e32 v1, 2, v33
	v_ashrrev_i32_e32 v5, 3, v33
	v_and_b32_e32 v38, 15, v33
	v_bfe_u32 v39, v33, 4, 2
	v_and_b32_e32 v32, -16, v1
	v_bfi_b32 v1, -16, v1, v33
	v_and_b32_e32 v41, 63, v33
	v_and_b32_e32 v34, -8, v5
	s_lshl_b32 s10, s10, 8
	v_mov_b32_e32 v0, 0
	v_mul_lo_u32 v1, v1, s30
	v_lshlrev_b32_e32 v2, 4, v39
	v_mul_u32_u24_e32 v3, 0x90, v38
	v_lshlrev_b32_e32 v42, 1, v41
	v_mul_lo_u32 v5, v34, s30
	s_add_u32 s10, s11, s10
	s_mov_b32 s3, 0
	v_cmp_gt_i32_e64 s[0:1], s99, v33
	v_ashrrev_i32_e32 v35, 31, v34
	v_add_u32_e32 v43, 0x200, v33
	v_cmp_lt_u32_e64 s[6:7], s40, v4
	s_addc_u32 s11, s12, 0
	s_mov_b64 s[14:15], -1
	v_add_u32_e32 v44, v42, v5
	v_add_u32_e32 v45, v1, v2
	v_add_u32_e32 v46, v2, v3
	v_mov_b32_e32 v1, v0
	v_mov_b32_e32 v2, v0
	v_mov_b32_e32 v3, v0
	v_mov_b32_e32 v4, v0
	v_mov_b32_e32 v5, v0
	v_mov_b32_e32 v6, v0
	v_mov_b32_e32 v7, v0
	v_mov_b32_e32 v8, v0
	v_mov_b32_e32 v9, v0
	v_mov_b32_e32 v10, v0
	v_mov_b32_e32 v11, v0
	v_mov_b32_e32 v12, v0
	v_mov_b32_e32 v13, v0
	v_mov_b32_e32 v14, v0
	v_mov_b32_e32 v15, v0
	v_mov_b32_e32 v16, v0
	v_mov_b32_e32 v17, v0
	v_mov_b32_e32 v18, v0
	v_mov_b32_e32 v19, v0
	v_mov_b32_e32 v20, v0
	v_mov_b32_e32 v21, v0
	v_mov_b32_e32 v22, v0
	v_mov_b32_e32 v23, v0
	v_mov_b32_e32 v24, v0
	v_mov_b32_e32 v25, v0
	v_mov_b32_e32 v26, v0
	v_mov_b32_e32 v27, v0
	v_mov_b32_e32 v28, v0
	v_mov_b32_e32 v29, v0
	v_mov_b32_e32 v30, v0
	v_mov_b32_e32 v31, v0
	s_branch .LBB0_491
